# early barrier K2 + HGRN scan two-group stagger by one barrier
# baseline (speedup 1.0000x reference)
.LBB0_887:
	s_lshl_b32 s6, s22, 1
	s_add_i32 s6, s6, s14
	s_ashr_i32 s7, s6, 31
	s_lshr_b32 s8, s7, 29
	s_add_i32 s8, s6, s8
	s_ashr_i32 s9, s8, 3
	s_lshr_b32 s11, s9, 28
	s_lshr_b32 s10, s7, 25
	s_add_i32 s11, s9, s11
	s_and_b32 s8, s8, 0x7ffff8
	s_add_i32 s10, s6, s10
	s_and_b32 s11, s11, 0x1fffff0
	s_sub_i32 s8, s6, s8
	s_sub_i32 s11, s9, s11
	s_lshl_b32 s9, s10, 5
	s_and_b32 s9, s9, 0xfffff000
	s_lshl_b32 s8, s8, 9
	s_add_i32 s8, s9, s8
	s_ashr_i32 s9, s8, 31
	s_lshl_b32 s10, s11, 7
	s_lshl_b64 s[8:9], s[8:9], 14
	s_ashr_i32 s11, s10, 31
	s_add_u32 s23, s12, s8
	s_addc_u32 s25, s13, s9
	s_lshl_b64 s[10:11], s[10:11], 1
	s_add_u32 s24, s23, s10
	s_addc_u32 s25, s25, s11
	v_lshl_add_u64 v[2:3], s[24:25], 0, v[118:119]
	v_lshl_add_u64 v[4:5], v[2:3], 0, v[106:107]
	v_add_co_u32_e32 v6, vcc, s17, v4
	v_lshl_add_u64 v[2:3], v[2:3], 0, v[108:109]
	s_nop 0
	v_addc_co_u32_e32 v7, vcc, 0, v5, vcc
	v_add_co_u32_e32 v2, vcc, s17, v2
	s_add_u32 s8, s8, s10
	s_nop 0
	v_addc_co_u32_e32 v3, vcc, 0, v3, vcc
	global_load_dwordx4 v[26:29], v[6:7], off
	global_load_dwordx4 v[30:33], v[2:3], off
	v_lshl_add_u64 v[2:3], s[24:25], 0, v[106:107]
	v_lshl_add_u64 v[2:3], v[2:3], 0, v[118:119]
	v_lshl_add_u64 v[6:7], s[24:25], 0, v[108:109]
	v_add_co_u32_e32 v2, vcc, s18, v2
	v_lshl_add_u64 v[6:7], v[6:7], 0, v[118:119]
	s_nop 0
	v_addc_co_u32_e32 v3, vcc, 0, v3, vcc
	v_add_co_u32_e32 v6, vcc, s18, v6
	s_addc_u32 s9, s9, s11
	s_nop 0
	v_addc_co_u32_e32 v7, vcc, 0, v7, vcc
	v_add_co_u32_e32 v8, vcc, s19, v4
	global_load_dwordx4 v[70:73], v[2:3], off
	global_load_dwordx4 v[78:81], v[6:7], off
	v_addc_co_u32_e32 v9, vcc, 0, v5, vcc
	v_add_co_u32_e32 v4, vcc, s20, v4
	v_mov_b32_e32 v143, 1.0
	s_nop 0
	v_addc_co_u32_e32 v5, vcc, 0, v5, vcc
	global_load_dwordx4 v[66:69], v[8:9], off
	global_load_dwordx4 v[74:77], v[4:5], off
	v_cmp_lt_i32_e32 vcc, v137, v136
	s_mov_b32 s23, 1
	v_mov_b32_e32 v2, 0
	s_waitcnt vmcnt(14)
	v_cndmask_b32_e32 v25, v135, v137, vcc
	v_mov_b32_e32 v3, v107
	v_mov_b32_e32 v4, v107
	v_mov_b32_e32 v5, v107
	v_mov_b32_e32 v6, v107
	v_mov_b32_e32 v7, v107
	v_mov_b32_e32 v8, v107
	v_mov_b32_e32 v9, v107
	v_mov_b32_e32 v10, v107
	v_mov_b32_e32 v11, v107
	v_mov_b32_e32 v12, v107
	v_mov_b32_e32 v13, v107
	v_mov_b32_e32 v14, v107
	v_mov_b32_e32 v15, v107
	v_mov_b32_e32 v16, v107
	v_mov_b32_e32 v17, v107
	v_mov_b32_e32 v18, 0
	v_mov_b32_e32 v19, v107
	v_mov_b32_e32 v20, v107
	v_mov_b32_e32 v21, v107
	v_mov_b32_e32 v22, v107
	v_mov_b32_e32 v23, v107
	v_mov_b32_e32 v24, v107
	v_lshlrev_b32_e32 v144, 2, v25
	v_lshl_add_u64 v[120:121], v[116:117], 0, s[8:9]
	v_mov_b32_e32 v25, v107
	v_mov_b32_e32 v34, 0
	v_mov_b32_e32 v35, v107
	v_mov_b32_e32 v36, v107
	v_mov_b32_e32 v37, v107
	v_mov_b32_e32 v38, v107
	v_mov_b32_e32 v39, v107
	v_mov_b32_e32 v40, v107
	v_mov_b32_e32 v41, v107
	v_mov_b32_e32 v42, v107
	v_mov_b32_e32 v43, v107
	s_waitcnt vmcnt(5)
	ds_write_b128 v111, v[26:29] offset:55296
	s_waitcnt vmcnt(4)
	ds_write_b128 v111, v[30:33] offset:59648
	s_waitcnt lgkmcnt(0)
	s_barrier
	v_mov_b32_e32 v26, v107
	v_mov_b32_e32 v27, v107
	v_mov_b32_e32 v28, v107
	v_mov_b32_e32 v29, v107
	v_mov_b32_e32 v30, v107
	v_mov_b32_e32 v31, v107
	v_mov_b32_e32 v32, v107
	v_mov_b32_e32 v33, v107
	v_mov_b32_e32 v44, v107
	v_mov_b32_e32 v45, v107
	v_mov_b32_e32 v46, v107
	v_mov_b32_e32 v47, v107
	v_mov_b32_e32 v48, v107
	v_mov_b32_e32 v49, v107
	v_mov_b32_e32 v50, 0
	v_mov_b32_e32 v51, v107
	v_mov_b32_e32 v52, v107
	v_mov_b32_e32 v53, v107
	v_mov_b32_e32 v54, v107
	v_mov_b32_e32 v55, v107
	v_mov_b32_e32 v56, v107
	v_mov_b32_e32 v57, v107
	v_mov_b32_e32 v58, v107
	v_mov_b32_e32 v59, v107
	v_mov_b32_e32 v60, v107
	v_mov_b32_e32 v61, v107
	v_mov_b32_e32 v62, v107
	v_mov_b32_e32 v63, v107
	v_mov_b32_e32 v64, v107
	v_mov_b32_e32 v65, v107
	v_readfirstlane_b32 s98, v0
	s_lshr_b32 s98, s98, 8
	s_cmp_eq_u32 s98, 0
	s_cbranch_scc1 .Lstg_pre_h1
	s_barrier
.Lstg_pre_h1:
	s_branch .LBB0_889
.LBB0_888:
	ds_read_b128 v[100:103], v145 offset:54848
	ds_read_b128 v[124:127], v145 offset:54880
	ds_read_b128 v[128:131], v145 offset:54784
	ds_read_b128 v[146:149], v145 offset:54816
	ds_read_b64_tr_b16 v[94:95], v141 offset:27648
	ds_read_b64_tr_b16 v[96:97], v141 offset:28928
	ds_read_b64_tr_b16 v[92:93], v141 offset:34048
	ds_read_b128 v[150:153], v142 offset:17408
	s_waitcnt lgkmcnt(6)
	v_pk_mul_f32 v[62:63], v[62:63], v[124:125]
	v_pk_mul_f32 v[58:59], v[58:59], v[100:101]
	s_waitcnt lgkmcnt(4)
	v_pk_mul_f32 v[54:55], v[54:55], v[146:147]
	v_pk_mul_f32 v[64:65], v[64:65], v[126:127]
	v_pk_mul_f32 v[60:61], v[60:61], v[102:103]
	v_pk_mul_f32 v[56:57], v[56:57], v[148:149]
	v_pk_mul_f32 v[52:53], v[52:53], v[130:131]
	v_pk_mul_f32 v[50:51], v[50:51], v[128:129]
	ds_read_b128 v[100:103], v142 offset:17440
	s_add_i32 s23, s23, 2
	s_waitcnt lgkmcnt(1)
	v_mfma_f32_32x32x16_bf16 v[50:65], v[150:153], v[94:97], v[50:65]
	ds_read_b64_tr_b16 v[90:91], v141 offset:32768
	ds_read_b128 v[124:127], v145 offset:55008
	ds_read_b128 v[128:131], v145 offset:54976
	ds_read_b128 v[146:149], v145 offset:54912
	ds_read_b128 v[150:153], v145 offset:54944
	s_cmp_gt_u32 s24, 13
	s_waitcnt lgkmcnt(3)
	v_pk_mul_f32 v[46:47], v[46:47], v[124:125]
	s_waitcnt lgkmcnt(2)
	v_pk_mul_f32 v[42:43], v[42:43], v[128:129]
	v_pk_mul_f32 v[48:49], v[48:49], v[126:127]
	s_waitcnt lgkmcnt(0)
	v_pk_mul_f32 v[38:39], v[38:39], v[150:151]
	v_pk_mul_f32 v[44:45], v[44:45], v[130:131]
	v_mfma_f32_32x32x16_bf16 v[50:65], v[100:103], v[90:93], v[50:65]
	ds_read_b128 v[100:103], v142 offset:19968
	ds_read_b128 v[124:127], v142 offset:20000
	v_mul_f32_e64 v40, v40, v152
	v_mul_f32_e64 v41, v41, v153
	v_mul_f32_e64 v36, v36, v148
	v_mul_f32_e64 v37, v37, v149
	v_pk_mul_f32 v[34:35], v[34:35], v[146:147]
	v_lshl_add_u64 v[120:121], v[120:121], 0, s[4:5]
	s_waitcnt lgkmcnt(1)
	v_mfma_f32_32x32x16_bf16 v[34:49], v[100:103], v[94:97], v[34:49]
	ds_read_b128 v[100:103], v145 offset:55136
	ds_read_b128 v[128:131], v145 offset:55104
	ds_read_b128 v[146:149], v145 offset:55040
	ds_read_b128 v[150:153], v145 offset:55072
	s_waitcnt lgkmcnt(3)
	v_pk_mul_f32 v[30:31], v[30:31], v[100:101]
	s_waitcnt lgkmcnt(2)
	v_pk_mul_f32 v[26:27], v[26:27], v[128:129]
	v_pk_mul_f32 v[32:33], v[32:33], v[102:103]
	s_waitcnt lgkmcnt(0)
	v_pk_mul_f32 v[22:23], v[22:23], v[150:151]
	v_pk_mul_f32 v[28:29], v[28:29], v[130:131]
	v_mfma_f32_32x32x16_bf16 v[34:49], v[124:127], v[90:93], v[34:49]
	ds_read_b128 v[124:127], v142 offset:22528
	ds_read_b128 v[100:103], v142 offset:22560
	v_mul_f32_e64 v24, v24, v152
	v_mul_f32_e64 v25, v25, v153
	v_mul_f32_e64 v20, v20, v148
	v_mul_f32_e64 v21, v21, v149
	v_pk_mul_f32 v[18:19], v[18:19], v[146:147]
	s_waitcnt lgkmcnt(1)
	s_nop 0
	v_mfma_f32_32x32x16_bf16 v[18:33], v[124:127], v[94:97], v[18:33]
	ds_read_b128 v[124:127], v145 offset:55264
	ds_read_b128 v[128:131], v145 offset:55232
	ds_read_b128 v[146:149], v145 offset:55168
	ds_read_b128 v[150:153], v145 offset:55200
	s_waitcnt lgkmcnt(3)
	v_pk_mul_f32 v[14:15], v[14:15], v[124:125]
	s_waitcnt lgkmcnt(2)
	v_pk_mul_f32 v[10:11], v[10:11], v[128:129]
	v_pk_mul_f32 v[16:17], v[16:17], v[126:127]
	s_waitcnt lgkmcnt(0)
	v_pk_mul_f32 v[6:7], v[6:7], v[150:151]
	v_pk_mul_f32 v[12:13], v[12:13], v[130:131]
	v_mfma_f32_32x32x16_bf16 v[18:33], v[100:103], v[90:93], v[18:33]
	ds_read_b128 v[100:103], v142 offset:25088
	ds_read_b128 v[124:127], v142 offset:25120
	v_mul_f32_e64 v8, v8, v152
	v_mul_f32_e64 v9, v9, v153
	v_mul_f32_e64 v4, v4, v148
	v_mul_f32_e64 v5, v5, v149
	v_pk_mul_f32 v[2:3], v[2:3], v[146:147]
	s_waitcnt lgkmcnt(0)
	s_barrier
	s_waitcnt lgkmcnt(1)
	v_mfma_f32_32x32x16_bf16 v[2:17], v[100:103], v[94:97], v[2:17]
	v_mul_f32_e32 v94, v143, v122
	v_mul_f32_e32 v143, v94, v98
	s_waitcnt lgkmcnt(0)
	v_mfma_f32_32x32x16_bf16 v[2:17], v[124:127], v[90:93], v[2:17]
	s_cbranch_scc1 .LBB0_901

.LBB0_901:
	s_cmp_lg_u32 s98, 0
	s_cbranch_scc1 .Lstg_post_h1
	s_barrier

.LBB0_966:
	s_or_b64 exec, exec, s[64:65]
	v_add_co_u32_e32 v98, vcc, 0x81000, v106
	v_lshl_add_u64 v[198:199], v[190:191], 0, s[0:1]
	s_nop 0
	v_addc_co_u32_e32 v99, vcc, 0, v107, vcc
	v_add_co_u32_e32 v102, vcc, 0x80000, v106
	v_lshl_add_u64 v[200:201], v[192:193], 0, s[0:1]
	s_nop 0
	v_addc_co_u32_e32 v103, vcc, 0, v107, vcc
	v_add_co_u32_e32 v108, vcc, 0xc1000, v106
	global_load_dwordx4 v[98:101], v[98:99], off
	s_nop 0
	global_load_dwordx4 v[102:105], v[102:103], off
	v_addc_co_u32_e32 v109, vcc, 0, v107, vcc
	v_add_co_u32_e32 v110, vcc, 0xc0000, v106
	s_lshl_b32 s0, s33, 9
	s_nop 0
	v_addc_co_u32_e32 v111, vcc, 0, v107, vcc
	global_load_dwordx4 v[106:109], v[108:109], off
	s_nop 0
	global_load_dwordx4 v[110:113], v[110:111], off
	s_waitcnt vmcnt(11)
	ds_write_b128 v215, v[66:69] offset:55296
	s_waitcnt vmcnt(10)
	ds_write_b128 v215, v[70:73] offset:64000
	s_waitcnt vmcnt(9)
	ds_write_b128 v215, v[74:77] offset:59648
	s_waitcnt vmcnt(8)
	ds_write_b128 v216, v[78:81] offset:64000
	v_and_b32_e32 v67, 64, v212
	v_xor_b32_e32 v66, 1, v212
	v_add_u32_e32 v67, 64, v67
	v_cmp_lt_i32_e32 vcc, v66, v67
	s_waitcnt lgkmcnt(0)
	s_barrier
	s_add_i32 s0, s0, s74
	v_cndmask_b32_e32 v66, v212, v66, vcc
	v_lshlrev_b32_e32 v195, 2, v66
	v_xor_b32_e32 v66, 2, v212
	v_cmp_lt_i32_e32 vcc, v66, v67
	s_mov_b32 s64, 1
	v_lshl_add_u64 v[196:197], v[188:189], 0, s[56:57]
	v_cndmask_b32_e32 v66, v212, v66, vcc
	v_lshlrev_b32_e32 v226, 2, v66
	v_xor_b32_e32 v66, 4, v212
	v_cmp_lt_i32_e32 vcc, v66, v67
	s_nop 1
	v_cndmask_b32_e32 v66, v212, v66, vcc
	v_lshlrev_b32_e32 v227, 2, v66
	v_add_u32_e32 v66, s0, v1
	s_lshl_b32 s0, s73, 12
	v_subrev_u32_e32 v202, s0, v66
	v_readfirstlane_b32 s98, v0
	s_lshr_b32 s98, s98, 8
	s_cmp_eq_u32 s98, 0
	s_cbranch_scc1 .Lstg_pre_h2
	s_barrier
.Lstg_pre_h2:
	s_branch .LBB0_968
.LBB0_967:
	ds_read_b128 v[66:69], v230 offset:8704
	ds_read_b128 v[70:73], v230
	ds_read_b128 v[138:141], v230 offset:32
	ds_read_b128 v[142:145], v230 offset:8736
	s_add_i32 s64, s64, 2
	v_lshl_add_u64 v[198:199], v[198:199], 0, s[48:49]
	s_waitcnt lgkmcnt(2)
	v_mfma_f32_32x32x16_bf16 v[66:81], v[66:69], v[70:73], 0
	v_lshl_add_u64 v[200:201], v[200:201], 0, s[48:49]
	s_cmp_lt_u32 s65, 14
	s_waitcnt lgkmcnt(0)
	v_mfma_f32_32x32x16_bf16 v[66:81], v[142:145], v[138:141], v[66:81]
	ds_read_b128 v[138:141], v230 offset:8768
	ds_read_b128 v[142:145], v230 offset:64
	s_waitcnt lgkmcnt(0)
	v_mfma_f32_32x32x16_bf16 v[66:81], v[138:141], v[142:145], v[66:81]
	ds_read_b128 v[138:141], v230 offset:8800
	ds_read_b128 v[142:145], v230 offset:96
	s_waitcnt lgkmcnt(0)
	v_mfma_f32_32x32x16_bf16 v[66:81], v[138:141], v[142:145], v[66:81]
	ds_read_b128 v[138:141], v230 offset:8832
	ds_read_b128 v[142:145], v230 offset:128
	s_waitcnt lgkmcnt(0)
	v_mfma_f32_32x32x16_bf16 v[66:81], v[138:141], v[142:145], v[66:81]
	ds_read_b128 v[138:141], v230 offset:8864
	ds_read_b128 v[142:145], v230 offset:160
	s_waitcnt lgkmcnt(0)
	v_mfma_f32_32x32x16_bf16 v[66:81], v[138:141], v[142:145], v[66:81]
	ds_read_b128 v[138:141], v230 offset:8896
	ds_read_b128 v[142:145], v230 offset:192
	s_waitcnt lgkmcnt(0)
	v_mfma_f32_32x32x16_bf16 v[66:81], v[138:141], v[142:145], v[66:81]
	ds_read_b128 v[138:141], v230 offset:8928
	ds_read_b128 v[142:145], v230 offset:224
	s_waitcnt lgkmcnt(0)
	v_mfma_f32_32x32x16_bf16 v[66:81], v[138:141], v[142:145], v[66:81]
	s_nop 11
	v_cndmask_b32_e64 v66, v66, 0, s[4:5]
	v_cndmask_b32_e64 v67, 0, v67, s[6:7]
	v_cndmask_b32_e64 v68, v68, 0, s[8:9]
	v_cndmask_b32_e64 v69, v69, 0, s[10:11]
	v_cndmask_b32_e64 v70, v70, 0, s[12:13]
	v_cndmask_b32_e64 v71, v71, 0, s[14:15]
	v_cndmask_b32_e64 v72, v72, 0, s[16:17]
	v_cndmask_b32_e64 v73, v73, 0, s[18:19]
	v_cvt_pk_bf16_f32 v66, v66, v67
	v_cvt_pk_bf16_f32 v67, v68, v69
	v_cvt_pk_bf16_f32 v68, v70, v71
	v_cvt_pk_bf16_f32 v69, v72, v73
	ds_read_b64_tr_b16 v[70:71], v221 offset:27648
	ds_read_b64_tr_b16 v[72:73], v221 offset:30208
	v_cndmask_b32_e64 v138, v74, 0, s[20:21]
	v_cndmask_b32_e64 v139, v75, 0, s[22:23]
	v_cndmask_b32_e64 v140, v76, 0, s[24:25]
	v_cndmask_b32_e64 v141, v77, 0, s[26:27]
	v_cndmask_b32_e64 v142, v78, 0, s[28:29]
	v_cndmask_b32_e64 v143, v79, 0, s[30:31]
	v_cndmask_b32_e64 v144, v80, 0, s[34:35]
	v_cndmask_b32_e64 v145, v81, 0, s[36:37]
	s_waitcnt lgkmcnt(0)
	v_mfma_f32_32x32x16_bf16 v[66:81], v[66:69], v[70:73], 0
	v_cvt_pk_bf16_f32 v138, v138, v139
	v_cvt_pk_bf16_f32 v139, v140, v141
	v_cvt_pk_bf16_f32 v140, v142, v143
	v_cvt_pk_bf16_f32 v141, v144, v145
	ds_read_b64_tr_b16 v[142:143], v221 offset:32768
	ds_read_b64_tr_b16 v[144:145], v221 offset:35328
	s_waitcnt lgkmcnt(0)
	v_mfma_f32_32x32x16_bf16 v[66:81], v[138:141], v[142:145], v[66:81]
	ds_read2_b64 v[142:145], v232 offset1:2
	ds_read2_b64 v[146:149], v232 offset0:4 offset1:6
	v_cvt_pk_bf16_f32 v138, v2, v3
	v_cvt_pk_bf16_f32 v139, v4, v5
	v_cvt_pk_bf16_f32 v140, v6, v7
	v_cvt_pk_bf16_f32 v141, v8, v9
	ds_read2_b64 v[150:153], v232 offset0:24 offset1:26
	s_waitcnt lgkmcnt(2)
	v_mfma_f32_32x32x16_bf16 v[66:81], v[142:145], v[138:141], v[66:81]
	v_cvt_pk_bf16_f32 v138, v10, v11
	v_cvt_pk_bf16_f32 v139, v12, v13
	v_cvt_pk_bf16_f32 v140, v14, v15
	v_cvt_pk_bf16_f32 v141, v16, v17
	ds_read2_b64 v[142:145], v232 offset0:8 offset1:10
	s_waitcnt lgkmcnt(2)
	v_mfma_f32_32x32x16_bf16 v[66:81], v[146:149], v[138:141], v[66:81]
	v_cvt_pk_bf16_f32 v138, v50, v51
	v_cvt_pk_bf16_f32 v139, v52, v53
	v_cvt_pk_bf16_f32 v140, v54, v55
	v_cvt_pk_bf16_f32 v141, v56, v57
	v_cvt_pk_bf16_f32 v146, v18, v19
	v_cvt_pk_bf16_f32 v147, v20, v21
	v_cvt_pk_bf16_f32 v148, v22, v23
	s_waitcnt lgkmcnt(0)
	v_mfma_f32_32x32x16_bf16 v[66:81], v[142:145], v[138:141], v[66:81]
	ds_read2_b64 v[142:145], v232 offset0:12 offset1:14
	v_cvt_pk_bf16_f32 v138, v58, v59
	v_cvt_pk_bf16_f32 v139, v60, v61
	v_cvt_pk_bf16_f32 v140, v62, v63
	v_cvt_pk_bf16_f32 v141, v64, v65
	v_cvt_pk_bf16_f32 v149, v24, v25
	s_waitcnt lgkmcnt(0)
	v_mfma_f32_32x32x16_bf16 v[66:81], v[142:145], v[138:141], v[66:81]
	ds_read2_b64 v[142:145], v232 offset0:16 offset1:18
	v_cvt_pk_bf16_f32 v138, v34, v35
	v_cvt_pk_bf16_f32 v139, v36, v37
	v_cvt_pk_bf16_f32 v140, v38, v39
	v_cvt_pk_bf16_f32 v141, v40, v41
	s_waitcnt lgkmcnt(0)
	s_nop 0
	v_mfma_f32_32x32x16_bf16 v[66:81], v[142:145], v[138:141], v[66:81]
	ds_read2_b64 v[142:145], v232 offset0:20 offset1:22
	v_cvt_pk_bf16_f32 v138, v42, v43
	v_cvt_pk_bf16_f32 v139, v44, v45
	v_cvt_pk_bf16_f32 v140, v46, v47
	v_cvt_pk_bf16_f32 v141, v48, v49
	s_waitcnt lgkmcnt(0)
	s_nop 0
	v_mfma_f32_32x32x16_bf16 v[66:81], v[142:145], v[138:141], v[66:81]
	ds_read2_b64 v[142:145], v232 offset0:28 offset1:30
	ds_read_b64_tr_b16 v[154:155], v222 offset:27648
	ds_read_b64_tr_b16 v[156:157], v222 offset:28928
	ds_read_b64_tr_b16 v[158:159], v222 offset:32768
	ds_read_b64_tr_b16 v[160:161], v222 offset:34048
	ds_read_b128 v[204:207], v228 offset:54784
	ds_read_b128 v[230:233], v228 offset:54816
	ds_read_b128 v[234:237], v228 offset:54848
	ds_read_b128 v[238:241], v228 offset:54880
	v_cvt_pk_bf16_f32 v138, v26, v27
	s_waitcnt lgkmcnt(3)
	v_pk_mul_f32 v[4:5], v[4:5], v[206:207]
	s_waitcnt lgkmcnt(2)
	v_pk_mul_f32 v[6:7], v[6:7], v[230:231]
	v_pk_mul_f32 v[8:9], v[8:9], v[232:233]
	v_pk_mul_f32 v[2:3], v[2:3], v[204:205]
	ds_read_b128 v[204:207], v223 offset:17408
	ds_read_b128 v[230:233], v223 offset:17440
	s_waitcnt lgkmcnt(2)
	v_pk_mul_f32 v[14:15], v[14:15], v[238:239]
	v_pk_mul_f32 v[10:11], v[10:11], v[234:235]
	v_pk_mul_f32 v[16:17], v[16:17], v[240:241]
	v_pk_mul_f32 v[12:13], v[12:13], v[236:237]
	v_mfma_f32_32x32x16_bf16 v[66:81], v[150:153], v[146:149], v[66:81]
	v_cvt_pk_bf16_f32 v139, v28, v29
	v_cvt_pk_bf16_f32 v140, v30, v31
	v_cvt_pk_bf16_f32 v141, v32, v33
	s_waitcnt lgkmcnt(1)
	v_mfma_f32_32x32x16_bf16 v[2:17], v[204:207], v[154:157], v[2:17]
	s_waitcnt lgkmcnt(0)
	v_mfma_f32_32x32x16_bf16 v[2:17], v[230:233], v[158:161], v[2:17]
	ds_read_b128 v[204:207], v228 offset:54912
	ds_read_b128 v[230:233], v228 offset:54944
	ds_read_b128 v[234:237], v228 offset:54976
	ds_read_b128 v[238:241], v228 offset:55008
	s_waitcnt lgkmcnt(3)
	v_pk_mul_f32 v[52:53], v[52:53], v[206:207]
	v_pk_mul_f32 v[50:51], v[50:51], v[204:205]
	ds_read_b128 v[204:207], v223 offset:19968
	s_waitcnt lgkmcnt(1)
	v_pk_mul_f32 v[62:63], v[62:63], v[238:239]
	v_pk_mul_f32 v[58:59], v[58:59], v[234:235]
	v_pk_mul_f32 v[54:55], v[54:55], v[230:231]
	v_pk_mul_f32 v[64:65], v[64:65], v[240:241]
	v_pk_mul_f32 v[60:61], v[60:61], v[236:237]
	v_pk_mul_f32 v[56:57], v[56:57], v[232:233]
	v_mfma_f32_32x32x16_bf16 v[66:81], v[142:145], v[138:141], v[66:81]
	s_waitcnt lgkmcnt(0)
	v_mfma_f32_32x32x16_bf16 v[50:65], v[204:207], v[154:157], v[50:65]
	ds_read_b128 v[204:207], v223 offset:20000
	s_waitcnt lgkmcnt(0)
	v_mfma_f32_32x32x16_bf16 v[50:65], v[204:207], v[158:161], v[50:65]
	ds_read_b128 v[204:207], v228 offset:55040
	ds_read_b128 v[230:233], v228 offset:55072
	ds_read_b128 v[234:237], v228 offset:55104
	ds_read_b128 v[238:241], v228 offset:55136
	s_waitcnt lgkmcnt(3)
	v_pk_mul_f32 v[36:37], v[36:37], v[206:207]
	v_pk_mul_f32 v[34:35], v[34:35], v[204:205]
	ds_read_b128 v[204:207], v223 offset:22528
	s_waitcnt lgkmcnt(1)
	v_pk_mul_f32 v[46:47], v[46:47], v[238:239]
	v_pk_mul_f32 v[42:43], v[42:43], v[234:235]
	v_pk_mul_f32 v[38:39], v[38:39], v[230:231]
	v_pk_mul_f32 v[48:49], v[48:49], v[240:241]
	v_pk_mul_f32 v[44:45], v[44:45], v[236:237]
	v_pk_mul_f32 v[40:41], v[40:41], v[232:233]
	s_waitcnt lgkmcnt(0)
	s_nop 0
	v_mfma_f32_32x32x16_bf16 v[34:49], v[204:207], v[154:157], v[34:49]
	ds_read_b128 v[204:207], v223 offset:22560
	s_waitcnt lgkmcnt(0)
	v_mfma_f32_32x32x16_bf16 v[34:49], v[204:207], v[158:161], v[34:49]
	ds_read_b128 v[204:207], v228 offset:55168
	ds_read_b128 v[230:233], v228 offset:55200
	ds_read_b128 v[234:237], v228 offset:55232
	ds_read_b128 v[238:241], v228 offset:55264
	s_waitcnt lgkmcnt(3)
	v_pk_mul_f32 v[20:21], v[20:21], v[206:207]
	v_pk_mul_f32 v[18:19], v[18:19], v[204:205]
	ds_read_b128 v[204:207], v223 offset:25088
	s_waitcnt lgkmcnt(1)
	v_pk_mul_f32 v[30:31], v[30:31], v[238:239]
	v_pk_mul_f32 v[26:27], v[26:27], v[234:235]
	v_pk_mul_f32 v[22:23], v[22:23], v[230:231]
	v_pk_mul_f32 v[32:33], v[32:33], v[240:241]
	v_pk_mul_f32 v[28:29], v[28:29], v[236:237]
	v_pk_mul_f32 v[24:25], v[24:25], v[232:233]
	s_waitcnt lgkmcnt(0)
	s_nop 0
	v_mfma_f32_32x32x16_bf16 v[18:33], v[204:207], v[154:157], v[18:33]
	ds_read_b128 v[154:157], v223 offset:25120
	ds_write2_b32 v163, v66, v67 offset1:132
	ds_write2_b32 v164, v68, v69 offset0:8 offset1:140
	ds_write2_b32 v165, v70, v71 offset0:32 offset1:164
	ds_write2_b32 v166, v72, v73 offset0:40 offset1:172
	ds_write2_b32 v167, v74, v75 offset0:64 offset1:196
	ds_write2_b32 v168, v76, v77 offset0:72 offset1:204
	ds_write2_b32 v169, v78, v79 offset0:96 offset1:228
	ds_write2_b32 v229, v80, v81 offset0:104 offset1:236
	s_waitcnt lgkmcnt(0)
	s_barrier
	ds_read_b128 v[66:69], v225 offset:37888
	ds_read_b128 v[70:73], v225 offset:37904
	ds_read_b128 v[74:77], v225 offset:37920
	ds_read_b128 v[78:81], v225 offset:37936
	s_waitcnt lgkmcnt(3)
	v_pk_mul_f32 v[138:139], v[68:69], v[68:69]
	v_pk_mul_f32 v[140:141], v[66:67], v[66:67]
	v_mfma_f32_32x32x16_bf16 v[18:33], v[154:157], v[158:161], v[18:33]
	v_pk_mov_b32 v[142:143], v[140:141], v[138:139] op_sel:[1,0]
	v_mov_b32_e32 v141, v139
	v_pk_add_f32 v[138:139], v[142:143], v[140:141]
	s_waitcnt lgkmcnt(2)
	v_pk_mul_f32 v[140:141], v[72:73], v[72:73]
	v_pk_mul_f32 v[142:143], v[70:71], v[70:71]
	v_pk_add_f32 v[138:139], v[138:139], v[138:139] op_sel:[0,1] op_sel_hi:[1,0]
	v_pk_mov_b32 v[144:145], v[142:143], v[140:141] op_sel:[1,0]
	v_mov_b32_e32 v143, v141
	v_pk_add_f32 v[140:141], v[144:145], v[142:143]
	s_waitcnt lgkmcnt(0)
	v_mul_f32_e32 v142, v78, v78
	v_mul_f32_e32 v143, v79, v79
	v_pk_add_f32 v[140:141], v[140:141], v[140:141] op_sel:[0,1] op_sel_hi:[1,0]
	v_mov_b32_e32 v139, v142
	v_mov_b32_e32 v141, v143
	v_pk_add_f32 v[138:139], v[138:139], v[140:141]
	v_mul_f32_e32 v140, v75, v75
	v_mul_f32_e32 v142, v77, v77
	v_mul_f32_e32 v144, v80, v80
	v_mul_f32_e32 v145, v81, v81
	v_pk_fma_f32 v[140:141], v[74:75], v[74:75], v[140:141] op_sel_hi:[1,1,0]
	v_pk_fma_f32 v[142:143], v[76:77], v[76:77], v[142:143] op_sel_hi:[1,1,0]
	v_mov_b32_e32 v141, v144
	v_mov_b32_e32 v143, v145
	v_pk_add_f32 v[140:141], v[140:141], v[142:143]
	s_nop 0
	v_pk_add_f32 v[138:139], v[138:139], v[140:141]
	s_nop 0
	v_add_f32_e32 v138, v138, v139
	ds_bpermute_b32 v139, v195, v138
	s_waitcnt lgkmcnt(0)
	v_add_f32_e32 v138, v138, v139
	ds_bpermute_b32 v139, v226, v138
	s_waitcnt lgkmcnt(0)
	v_add_f32_e32 v138, v138, v139
	ds_bpermute_b32 v139, v227, v138
	s_waitcnt lgkmcnt(0)
	v_add_f32_e32 v138, v138, v139
	v_fmamk_f32 v138, v138, 0x3c000000, v213
	v_cmp_gt_f32_e32 vcc, s94, v138
	v_mul_f32_e32 v139, 0x4f800000, v138
	s_nop 0
	v_cndmask_b32_e32 v138, v138, v139, vcc
	v_sqrt_f32_e32 v139, v138
	s_nop 0
	v_add_u32_e32 v140, -1, v139
	v_fma_f32 v141, -v140, v139, v138
	v_cmp_ge_f32_e64 s[0:1], 0, v141
	v_add_u32_e32 v141, 1, v139
	s_nop 0
	v_cndmask_b32_e64 v140, v139, v140, s[0:1]
	v_fma_f32 v139, -v141, v139, v138
	v_cmp_lt_f32_e64 s[0:1], 0, v139
	s_nop 1
	v_cndmask_b32_e64 v139, v140, v141, s[0:1]
	v_mul_f32_e32 v140, 0x37800000, v139
	v_cndmask_b32_e32 v139, v139, v140, vcc
	v_cmp_class_f32_e32 vcc, v138, v214
	s_nop 1
	v_cndmask_b32_e32 v138, v139, v138, vcc
	v_div_scale_f32 v139, s[0:1], v138, v138, 1.0
	v_rcp_f32_e32 v140, v139
	s_nop 0
	v_fma_f32 v141, -v139, v140, 1.0
	v_fmac_f32_e32 v140, v141, v140
	v_div_scale_f32 v141, vcc, 1.0, v138, 1.0
	v_mul_f32_e32 v142, v141, v140
	v_fma_f32 v143, -v139, v142, v141
	v_fmac_f32_e32 v142, v143, v140
	v_fma_f32 v139, -v139, v142, v141
	v_div_fmas_f32 v139, v139, v140, v142
	v_div_fixup_f32 v150, v139, v138, 1.0
	v_pk_mul_f32 v[152:153], v[66:67], v[150:151] op_sel_hi:[1,0]
	v_pk_mul_f32 v[154:155], v[68:69], v[150:151] op_sel_hi:[1,0]
	ds_read_b128 v[66:69], v162
	ds_read_b128 v[138:141], v162 offset:16
	ds_read_b128 v[142:145], v162 offset:32
	ds_read_b128 v[146:149], v162 offset:48
	v_pk_mul_f32 v[70:71], v[70:71], v[150:151] op_sel_hi:[1,0]
	s_waitcnt lgkmcnt(3)
	v_pk_mul_f32 v[66:67], v[66:67], v[152:153]
	s_waitcnt lgkmcnt(2)
	v_pk_mul_f32 v[70:71], v[138:139], v[70:71]
	s_waitcnt vmcnt(3)
	v_and_b32_e32 v139, 0xffff0000, v134
	v_lshlrev_b32_e32 v138, 16, v134
	v_pk_mul_f32 v[68:69], v[68:69], v[154:155]
	v_pk_mul_f32 v[66:67], v[66:67], v[138:139]
	v_and_b32_e32 v139, 0xffff0000, v135
	v_lshlrev_b32_e32 v138, 16, v135
	v_pk_mul_f32 v[68:69], v[68:69], v[138:139]
	v_pk_mul_f32 v[72:73], v[72:73], v[150:151] op_sel_hi:[1,0]
	v_cvt_pk_bf16_f32 v66, v66, v67
	v_cvt_pk_bf16_f32 v67, v68, v69
	v_and_b32_e32 v69, 0xffff0000, v136
	v_lshlrev_b32_e32 v68, 16, v136
	v_pk_mul_f32 v[72:73], v[140:141], v[72:73]
	v_pk_mul_f32 v[68:69], v[70:71], v[68:69]
	v_and_b32_e32 v71, 0xffff0000, v137
	v_lshlrev_b32_e32 v70, 16, v137
	v_pk_mul_f32 v[70:71], v[72:73], v[70:71]
	v_cvt_pk_bf16_f32 v68, v68, v69
	v_cvt_pk_bf16_f32 v69, v70, v71
	v_pk_mul_f32 v[70:71], v[74:75], v[150:151] op_sel_hi:[1,0]
	v_pk_mul_f32 v[72:73], v[76:77], v[150:151] op_sel_hi:[1,0]
	s_waitcnt lgkmcnt(1)
	v_pk_mul_f32 v[70:71], v[142:143], v[70:71]
	v_pk_mul_f32 v[74:75], v[78:79], v[150:151] op_sel_hi:[1,0]
	s_waitcnt vmcnt(2)
	v_and_b32_e32 v79, 0xffff0000, v130
	v_lshlrev_b32_e32 v78, 16, v130
	v_pk_mul_f32 v[72:73], v[144:145], v[72:73]
	v_pk_mul_f32 v[70:71], v[70:71], v[78:79]
	v_and_b32_e32 v79, 0xffff0000, v131
	v_lshlrev_b32_e32 v78, 16, v131
	v_pk_mul_f32 v[72:73], v[72:73], v[78:79]
	v_pk_mul_f32 v[76:77], v[80:81], v[150:151] op_sel_hi:[1,0]
	s_waitcnt lgkmcnt(0)
	v_pk_mul_f32 v[74:75], v[146:147], v[74:75]
	v_cvt_pk_bf16_f32 v70, v70, v71
	v_cvt_pk_bf16_f32 v71, v72, v73
	v_and_b32_e32 v73, 0xffff0000, v132
	v_lshlrev_b32_e32 v72, 16, v132
	v_pk_mul_f32 v[76:77], v[148:149], v[76:77]
	v_pk_mul_f32 v[72:73], v[74:75], v[72:73]
	v_and_b32_e32 v75, 0xffff0000, v133
	v_lshlrev_b32_e32 v74, 16, v133
	v_pk_mul_f32 v[74:75], v[76:77], v[74:75]
	v_cvt_pk_bf16_f32 v72, v72, v73
	v_cvt_pk_bf16_f32 v73, v74, v75
	v_add_u32_e32 v74, 32, v202
	v_ashrrev_i32_e32 v75, 31, v74
	v_lshlrev_b64 v[74:75], 12, v[74:75]
	v_lshl_add_u64 v[74:75], v[196:197], 0, v[74:75]
	v_add_u32_e32 v202, 64, v202
	global_store_dwordx4 v[74:75], v[66:69], off
	global_store_dwordx4 v[74:75], v[70:73], off offset:16
	s_cbranch_scc0 .LBB0_960

	.amdhsa_kernel _Z8mega_fwd4Args
		.amdhsa_group_segment_fixed_size 0
		.amdhsa_private_segment_fixed_size 0
		.amdhsa_kernarg_size 456
		.amdhsa_user_sgpr_count 2
		.amdhsa_user_sgpr_dispatch_ptr 0
		.amdhsa_user_sgpr_queue_ptr 0
		.amdhsa_user_sgpr_kernarg_segment_ptr 1
		.amdhsa_user_sgpr_dispatch_id 0
		.amdhsa_user_sgpr_kernarg_preload_length 0
		.amdhsa_user_sgpr_kernarg_preload_offset 0
		.amdhsa_user_sgpr_private_segment_size 0
		.amdhsa_uses_dynamic_stack 0
		.amdhsa_enable_private_segment 0
		.amdhsa_system_sgpr_workgroup_id_x 1
		.amdhsa_system_sgpr_workgroup_id_y 0
		.amdhsa_system_sgpr_workgroup_id_z 0
		.amdhsa_system_sgpr_workgroup_info 0
		.amdhsa_system_vgpr_workitem_id 0
		.amdhsa_next_free_vgpr 251
		.amdhsa_next_free_sgpr 102
		.amdhsa_accum_offset 252
		.amdhsa_reserve_vcc 1
		.amdhsa_float_round_mode_32 0
		.amdhsa_float_round_mode_16_64 0
		.amdhsa_float_denorm_mode_32 3
		.amdhsa_float_denorm_mode_16_64 3
		.amdhsa_dx10_clamp 1
		.amdhsa_ieee_mode 1
		.amdhsa_fp16_overflow 0
		.amdhsa_tg_split 0
		.amdhsa_exception_fp_ieee_invalid_op 0
		.amdhsa_exception_fp_denorm_src 0
		.amdhsa_exception_fp_ieee_div_zero 0
		.amdhsa_exception_fp_ieee_overflow 0
		.amdhsa_exception_fp_ieee_underflow 0
		.amdhsa_exception_fp_ieee_inexact 0
		.amdhsa_exception_int_div_zero 0
	.end_amdhsa_kernel

amdhsa.kernels:
  - .agpr_count:     0
    .args:
      - .offset:         0
        .size:           200
        .value_kind:     by_value
      - .offset:         200
        .size:           4
        .value_kind:     hidden_block_count_x
      - .offset:         204
        .size:           4
        .value_kind:     hidden_block_count_y
      - .offset:         208
        .size:           4
        .value_kind:     hidden_block_count_z
      - .offset:         212
        .size:           2
        .value_kind:     hidden_group_size_x
      - .offset:         214
        .size:           2
        .value_kind:     hidden_group_size_y
      - .offset:         216
        .size:           2
        .value_kind:     hidden_group_size_z
      - .offset:         218
        .size:           2
        .value_kind:     hidden_remainder_x
      - .offset:         220
        .size:           2
        .value_kind:     hidden_remainder_y
      - .offset:         222
        .size:           2
        .value_kind:     hidden_remainder_z
      - .offset:         240
        .size:           8
        .value_kind:     hidden_global_offset_x
      - .offset:         248
        .size:           8
        .value_kind:     hidden_global_offset_y
      - .offset:         256
        .size:           8
        .value_kind:     hidden_global_offset_z
      - .offset:         264
        .size:           2
        .value_kind:     hidden_grid_dims
      - .offset:         320
        .size:           4
        .value_kind:     hidden_dynamic_lds_size
    .group_segment_fixed_size: 0
    .kernarg_segment_align: 8
    .kernarg_segment_size: 456
    .language:       OpenCL C
    .language_version:
      - 2
      - 0
    .max_flat_workgroup_size: 512
    .name:           _Z8mega_fwd4Args
    .private_segment_fixed_size: 0
    .sgpr_count:     108
    .sgpr_spill_count: 22
    .symbol:         _Z8mega_fwd4Args.kd
    .uniform_work_group_size: 1
    .uses_dynamic_stack: false
    .vgpr_count:     251
    .vgpr_spill_count: 0
    .wavefront_size: 64
